# mods_units silu-table loop: six loads issued together, pointers loaded once; redundant vmcnt(0) store-ack waits removed in residual and in-proj epilogues
# speedup vs baseline: 1.0401x; 1.0401x over previous
.LBB0_505:
	s_andn2_b64 vcc, exec, s[4:5]
	s_cbranch_vccnz .LBB0_507
	v_sub_f32_e32 v2, 1.0, v162
	v_fma_f32 v2, v2, v230, v162
	v_sub_f32_e32 v3, 1.0, v166
	v_sub_f32_e32 v4, 1.0, v163
	v_fma_f32 v3, v3, v232, v166
	v_fma_f32 v4, v4, v231, v163
	v_sub_f32_e32 v5, 1.0, v167
	v_sub_f32_e32 v8, 1.0, v165
	v_log_f32_e32 v2, v2
	v_fma_f32 v5, v5, v233, v167
	v_sub_f32_e32 v6, 1.0, v164
	v_sub_f32_e32 v7, 1.0, v168
	v_fma_f32 v8, v8, v207, v165
	v_sub_f32_e32 v9, 1.0, v169
	v_log_f32_e32 v4, v4
	v_log_f32_e32 v207, v3
	v_fma_f32 v6, v6, v206, v164
	v_fma_f32 v7, v7, v208, v168
	v_fma_f32 v9, v9, v209, v169
	v_log_f32_e32 v8, v8
	v_log_f32_e32 v5, v5
	v_log_f32_e32 v206, v6
	v_log_f32_e32 v208, v7
	v_log_f32_e32 v209, v9
	v_mul_f32_e32 v2, 0x3f317218, v2
	v_max_f32_e32 v6, 0xc2a00000, v2
	v_mul_f32_e32 v2, 0x3f317218, v4
	v_mul_f32_e32 v4, 0x3f317218, v207
	v_mul_f32_e32 v3, 0x3f317218, v8
	v_max_f32_e32 v8, 0xc2a00000, v4
	v_mul_f32_e32 v4, 0x3f317218, v5
	v_max_f32_e32 v7, 0xc2a00000, v2
	v_mul_f32_e32 v2, 0x3f317218, v206
	v_max_f32_e32 v9, 0xc2a00000, v4
	v_mul_f32_e32 v4, 0x3f317218, v208
	v_mul_f32_e32 v5, 0x3f317218, v209
	v_max_f32_e32 v2, 0xc2a00000, v2
	v_max_f32_e32 v3, 0xc2a00000, v3
	v_max_f32_e32 v4, 0xc2a00000, v4
	v_max_f32_e32 v5, 0xc2a00000, v5

.LBB0_508:
	s_andn2_b64 vcc, exec, s[4:5]
	s_cbranch_vccnz .LBB0_511
	v_pk_mul_f32 v[2:3], v[196:197], v[128:129]
	v_pk_mul_f32 v[4:5], v[194:195], v[126:127]
	v_pk_mul_f32 v[6:7], v[200:201], v[128:129]
	v_pk_mul_f32 v[8:9], v[198:199], v[126:127]
	v_pk_fma_f32 v[2:3], v[200:201], v[124:125], v[2:3] neg_lo:[0,0,1] neg_hi:[0,0,1]
	v_pk_fma_f32 v[4:5], v[198:199], v[122:123], v[4:5] neg_lo:[0,0,1] neg_hi:[0,0,1]
	v_pk_fma_f32 v[206:207], v[196:197], v[124:125], v[6:7]
	v_pk_fma_f32 v[8:9], v[194:195], v[122:123], v[8:9]
	v_cndmask_b32_e64 v3, v201, v3, s[10:11]
	v_cndmask_b32_e64 v2, v200, v2, s[10:11]
	v_cndmask_b32_e64 v7, v199, v5, s[10:11]
	v_cndmask_b32_e64 v6, v198, v4, s[10:11]
	v_cndmask_b32_e64 v5, v197, v207, s[10:11]
	v_cndmask_b32_e64 v4, v196, v206, s[10:11]
	v_cndmask_b32_e64 v9, v195, v9, s[10:11]
	s_and_b64 vcc, exec, s[14:15]
	v_cndmask_b32_e64 v8, v194, v8, s[10:11]
	s_cbranch_vccnz .LBB0_511
	v_pk_mul_f32 v[2:3], v[2:3], s[56:57] op_sel_hi:[1,0]
	v_pk_mul_f32 v[6:7], v[6:7], s[56:57] op_sel_hi:[1,0]
	v_pk_mul_f32 v[4:5], v[4:5], s[56:57] op_sel_hi:[1,0]
	v_pk_mul_f32 v[8:9], v[8:9], s[56:57] op_sel_hi:[1,0]

.LBB0_519:
	s_andn2_b64 vcc, exec, s[4:5]
	s_cbranch_vccnz .LBB0_521
	v_sub_f32_e32 v2, 1.0, v162
	v_fma_f32 v2, v2, v200, v162
	v_sub_f32_e32 v3, 1.0, v166
	v_sub_f32_e32 v4, 1.0, v163
	v_fma_f32 v3, v3, v206, v166
	v_fma_f32 v4, v4, v201, v163
	v_sub_f32_e32 v5, 1.0, v167
	v_sub_f32_e32 v8, 1.0, v165
	v_log_f32_e32 v2, v2
	v_fma_f32 v5, v5, v207, v167
	v_sub_f32_e32 v6, 1.0, v164
	v_sub_f32_e32 v7, 1.0, v168
	v_fma_f32 v8, v8, v197, v165
	v_sub_f32_e32 v9, 1.0, v169
	v_log_f32_e32 v4, v4
	v_log_f32_e32 v197, v3
	v_fma_f32 v6, v6, v196, v164
	v_fma_f32 v7, v7, v198, v168
	v_fma_f32 v9, v9, v199, v169
	v_log_f32_e32 v8, v8
	v_log_f32_e32 v5, v5
	v_log_f32_e32 v196, v6
	v_log_f32_e32 v198, v7
	v_log_f32_e32 v199, v9
	v_mul_f32_e32 v2, 0x3f317218, v2
	v_max_f32_e32 v6, 0xc2a00000, v2
	v_mul_f32_e32 v2, 0x3f317218, v4
	v_mul_f32_e32 v4, 0x3f317218, v197
	v_mul_f32_e32 v3, 0x3f317218, v8
	v_max_f32_e32 v8, 0xc2a00000, v4
	v_mul_f32_e32 v4, 0x3f317218, v5
	v_max_f32_e32 v7, 0xc2a00000, v2
	v_mul_f32_e32 v2, 0x3f317218, v196
	v_max_f32_e32 v9, 0xc2a00000, v4
	v_mul_f32_e32 v4, 0x3f317218, v198
	v_mul_f32_e32 v5, 0x3f317218, v199
	v_max_f32_e32 v2, 0xc2a00000, v2
	v_max_f32_e32 v3, 0xc2a00000, v3
	v_max_f32_e32 v4, 0xc2a00000, v4
	v_max_f32_e32 v5, 0xc2a00000, v5

.LBB0_522:
	s_andn2_b64 vcc, exec, s[4:5]
	s_cbranch_vccnz .LBB0_525
	v_pk_mul_f32 v[2:3], v[188:189], v[120:121]
	v_pk_mul_f32 v[4:5], v[186:187], v[118:119]
	v_pk_mul_f32 v[6:7], v[192:193], v[120:121]
	v_pk_mul_f32 v[8:9], v[190:191], v[118:119]
	v_pk_fma_f32 v[2:3], v[192:193], v[116:117], v[2:3] neg_lo:[0,0,1] neg_hi:[0,0,1]
	v_pk_fma_f32 v[4:5], v[190:191], v[114:115], v[4:5] neg_lo:[0,0,1] neg_hi:[0,0,1]
	v_pk_fma_f32 v[196:197], v[188:189], v[116:117], v[6:7]
	v_pk_fma_f32 v[8:9], v[186:187], v[114:115], v[8:9]
	v_cndmask_b32_e64 v3, v193, v3, s[10:11]
	v_cndmask_b32_e64 v2, v192, v2, s[10:11]
	v_cndmask_b32_e64 v7, v191, v5, s[10:11]
	v_cndmask_b32_e64 v6, v190, v4, s[10:11]
	v_cndmask_b32_e64 v5, v189, v197, s[10:11]
	v_cndmask_b32_e64 v4, v188, v196, s[10:11]
	v_cndmask_b32_e64 v9, v187, v9, s[10:11]
	s_and_b64 vcc, exec, s[14:15]
	v_cndmask_b32_e64 v8, v186, v8, s[10:11]
	s_cbranch_vccnz .LBB0_525
	v_pk_mul_f32 v[2:3], v[2:3], s[56:57] op_sel_hi:[1,0]
	v_pk_mul_f32 v[6:7], v[6:7], s[56:57] op_sel_hi:[1,0]
	v_pk_mul_f32 v[4:5], v[4:5], s[56:57] op_sel_hi:[1,0]
	v_pk_mul_f32 v[8:9], v[8:9], s[56:57] op_sel_hi:[1,0]

.LBB0_533:
	s_andn2_b64 vcc, exec, s[4:5]
	s_cbranch_vccnz .LBB0_535
	v_sub_f32_e32 v2, 1.0, v162
	v_fma_f32 v2, v2, v192, v162
	v_sub_f32_e32 v3, 1.0, v166
	v_sub_f32_e32 v4, 1.0, v163
	v_fma_f32 v3, v3, v196, v166
	v_fma_f32 v4, v4, v193, v163
	v_sub_f32_e32 v5, 1.0, v167
	v_sub_f32_e32 v8, 1.0, v165
	v_log_f32_e32 v2, v2
	v_fma_f32 v5, v5, v197, v167
	v_sub_f32_e32 v6, 1.0, v164
	v_sub_f32_e32 v7, 1.0, v168
	v_fma_f32 v8, v8, v189, v165
	v_sub_f32_e32 v9, 1.0, v169
	v_log_f32_e32 v4, v4
	v_log_f32_e32 v189, v3
	v_fma_f32 v6, v6, v188, v164
	v_fma_f32 v7, v7, v190, v168
	v_fma_f32 v9, v9, v191, v169
	v_log_f32_e32 v8, v8
	v_log_f32_e32 v5, v5
	v_log_f32_e32 v188, v6
	v_log_f32_e32 v190, v7
	v_log_f32_e32 v191, v9
	v_mul_f32_e32 v2, 0x3f317218, v2
	v_max_f32_e32 v6, 0xc2a00000, v2
	v_mul_f32_e32 v2, 0x3f317218, v4
	v_mul_f32_e32 v4, 0x3f317218, v189
	v_mul_f32_e32 v3, 0x3f317218, v8
	v_max_f32_e32 v8, 0xc2a00000, v4
	v_mul_f32_e32 v4, 0x3f317218, v5
	v_max_f32_e32 v7, 0xc2a00000, v2
	v_mul_f32_e32 v2, 0x3f317218, v188
	v_max_f32_e32 v9, 0xc2a00000, v4
	v_mul_f32_e32 v4, 0x3f317218, v190
	v_mul_f32_e32 v5, 0x3f317218, v191
	v_max_f32_e32 v2, 0xc2a00000, v2
	v_max_f32_e32 v3, 0xc2a00000, v3
	v_max_f32_e32 v4, 0xc2a00000, v4
	v_max_f32_e32 v5, 0xc2a00000, v5

.LBB0_536:
	s_andn2_b64 vcc, exec, s[4:5]
	s_cbranch_vccnz .LBB0_539
	v_pk_mul_f32 v[2:3], v[180:181], v[104:105]
	v_pk_mul_f32 v[4:5], v[178:179], v[102:103]
	v_pk_mul_f32 v[6:7], v[184:185], v[104:105]
	v_pk_mul_f32 v[8:9], v[182:183], v[102:103]
	v_pk_fma_f32 v[2:3], v[184:185], v[100:101], v[2:3] neg_lo:[0,0,1] neg_hi:[0,0,1]
	v_pk_fma_f32 v[4:5], v[182:183], v[98:99], v[4:5] neg_lo:[0,0,1] neg_hi:[0,0,1]
	v_pk_fma_f32 v[188:189], v[180:181], v[100:101], v[6:7]
	v_pk_fma_f32 v[8:9], v[178:179], v[98:99], v[8:9]
	v_cndmask_b32_e64 v3, v185, v3, s[10:11]
	v_cndmask_b32_e64 v2, v184, v2, s[10:11]
	v_cndmask_b32_e64 v7, v183, v5, s[10:11]
	v_cndmask_b32_e64 v6, v182, v4, s[10:11]
	v_cndmask_b32_e64 v5, v181, v189, s[10:11]
	v_cndmask_b32_e64 v4, v180, v188, s[10:11]
	v_cndmask_b32_e64 v9, v179, v9, s[10:11]
	s_and_b64 vcc, exec, s[14:15]
	v_cndmask_b32_e64 v8, v178, v8, s[10:11]
	s_cbranch_vccnz .LBB0_539
	v_pk_mul_f32 v[2:3], v[2:3], s[56:57] op_sel_hi:[1,0]
	v_pk_mul_f32 v[6:7], v[6:7], s[56:57] op_sel_hi:[1,0]
	v_pk_mul_f32 v[4:5], v[4:5], s[56:57] op_sel_hi:[1,0]
	v_pk_mul_f32 v[8:9], v[8:9], s[56:57] op_sel_hi:[1,0]

.LBB0_547:
	s_andn2_b64 vcc, exec, s[4:5]
	s_cbranch_vccnz .LBB0_549
	v_sub_f32_e32 v2, 1.0, v162
	v_fma_f32 v2, v2, v184, v162
	v_sub_f32_e32 v3, 1.0, v166
	v_sub_f32_e32 v4, 1.0, v163
	v_fma_f32 v3, v3, v188, v166
	v_fma_f32 v4, v4, v185, v163
	v_sub_f32_e32 v5, 1.0, v167
	v_sub_f32_e32 v8, 1.0, v165
	v_log_f32_e32 v2, v2
	v_fma_f32 v5, v5, v189, v167
	v_sub_f32_e32 v6, 1.0, v164
	v_sub_f32_e32 v7, 1.0, v168
	v_fma_f32 v8, v8, v181, v165
	v_sub_f32_e32 v9, 1.0, v169
	v_log_f32_e32 v4, v4
	v_log_f32_e32 v181, v3
	v_fma_f32 v6, v6, v180, v164
	v_fma_f32 v7, v7, v182, v168
	v_fma_f32 v9, v9, v183, v169
	v_log_f32_e32 v8, v8
	v_log_f32_e32 v5, v5
	v_log_f32_e32 v180, v6
	v_log_f32_e32 v182, v7
	v_log_f32_e32 v183, v9
	v_mul_f32_e32 v2, 0x3f317218, v2
	v_max_f32_e32 v6, 0xc2a00000, v2
	v_mul_f32_e32 v2, 0x3f317218, v4
	v_mul_f32_e32 v4, 0x3f317218, v181
	v_mul_f32_e32 v3, 0x3f317218, v8
	v_max_f32_e32 v8, 0xc2a00000, v4
	v_mul_f32_e32 v4, 0x3f317218, v5
	v_max_f32_e32 v7, 0xc2a00000, v2
	v_mul_f32_e32 v2, 0x3f317218, v180
	v_max_f32_e32 v9, 0xc2a00000, v4
	v_mul_f32_e32 v4, 0x3f317218, v182
	v_mul_f32_e32 v5, 0x3f317218, v183
	v_max_f32_e32 v2, 0xc2a00000, v2
	v_max_f32_e32 v3, 0xc2a00000, v3
	v_max_f32_e32 v4, 0xc2a00000, v4
	v_max_f32_e32 v5, 0xc2a00000, v5

.LBB0_550:
	s_andn2_b64 vcc, exec, s[4:5]
	s_cbranch_vccnz .LBB0_553
	v_pk_mul_f32 v[2:3], v[172:173], v[88:89]
	v_pk_mul_f32 v[4:5], v[170:171], v[86:87]
	v_pk_mul_f32 v[6:7], v[176:177], v[88:89]
	v_pk_mul_f32 v[8:9], v[174:175], v[86:87]
	v_pk_fma_f32 v[2:3], v[176:177], v[84:85], v[2:3] neg_lo:[0,0,1] neg_hi:[0,0,1]
	v_pk_fma_f32 v[4:5], v[174:175], v[82:83], v[4:5] neg_lo:[0,0,1] neg_hi:[0,0,1]
	v_pk_fma_f32 v[180:181], v[172:173], v[84:85], v[6:7]
	v_pk_fma_f32 v[8:9], v[170:171], v[82:83], v[8:9]
	v_cndmask_b32_e64 v3, v177, v3, s[10:11]
	v_cndmask_b32_e64 v2, v176, v2, s[10:11]
	v_cndmask_b32_e64 v7, v175, v5, s[10:11]
	v_cndmask_b32_e64 v6, v174, v4, s[10:11]
	v_cndmask_b32_e64 v5, v173, v181, s[10:11]
	v_cndmask_b32_e64 v4, v172, v180, s[10:11]
	v_cndmask_b32_e64 v9, v171, v9, s[10:11]
	s_and_b64 vcc, exec, s[14:15]
	v_cndmask_b32_e64 v8, v170, v8, s[10:11]
	s_cbranch_vccnz .LBB0_553
	v_pk_mul_f32 v[2:3], v[2:3], s[56:57] op_sel_hi:[1,0]
	v_pk_mul_f32 v[6:7], v[6:7], s[56:57] op_sel_hi:[1,0]
	v_pk_mul_f32 v[4:5], v[4:5], s[56:57] op_sel_hi:[1,0]
	v_pk_mul_f32 v[8:9], v[8:9], s[56:57] op_sel_hi:[1,0]

.LBB0_561:
	s_andn2_b64 vcc, exec, s[4:5]
	s_cbranch_vccnz .LBB0_563
	v_sub_f32_e32 v2, 1.0, v162
	v_fma_f32 v2, v2, v176, v162
	v_sub_f32_e32 v3, 1.0, v166
	v_sub_f32_e32 v4, 1.0, v163
	v_fma_f32 v3, v3, v180, v166
	v_fma_f32 v4, v4, v177, v163
	v_sub_f32_e32 v5, 1.0, v167
	v_sub_f32_e32 v8, 1.0, v165
	v_log_f32_e32 v2, v2
	v_fma_f32 v5, v5, v181, v167
	v_sub_f32_e32 v6, 1.0, v164
	v_sub_f32_e32 v7, 1.0, v168
	v_fma_f32 v8, v8, v173, v165
	v_sub_f32_e32 v9, 1.0, v169
	v_log_f32_e32 v4, v4
	v_log_f32_e32 v173, v3
	v_fma_f32 v6, v6, v172, v164
	v_fma_f32 v7, v7, v174, v168
	v_fma_f32 v9, v9, v175, v169
	v_log_f32_e32 v8, v8
	v_log_f32_e32 v5, v5
	v_log_f32_e32 v172, v6
	v_log_f32_e32 v174, v7
	v_log_f32_e32 v175, v9
	v_mul_f32_e32 v2, 0x3f317218, v2
	v_max_f32_e32 v6, 0xc2a00000, v2
	v_mul_f32_e32 v2, 0x3f317218, v4
	v_mul_f32_e32 v4, 0x3f317218, v173
	v_mul_f32_e32 v3, 0x3f317218, v8
	v_max_f32_e32 v8, 0xc2a00000, v4
	v_mul_f32_e32 v4, 0x3f317218, v5
	v_max_f32_e32 v7, 0xc2a00000, v2
	v_mul_f32_e32 v2, 0x3f317218, v172
	v_max_f32_e32 v9, 0xc2a00000, v4
	v_mul_f32_e32 v4, 0x3f317218, v174
	v_mul_f32_e32 v5, 0x3f317218, v175
	v_max_f32_e32 v2, 0xc2a00000, v2
	v_max_f32_e32 v3, 0xc2a00000, v3
	v_max_f32_e32 v4, 0xc2a00000, v4
	v_max_f32_e32 v5, 0xc2a00000, v5

.LBB0_564:
	s_andn2_b64 vcc, exec, s[4:5]
	s_cbranch_vccnz .LBB0_567
	v_pk_mul_f32 v[2:3], v[156:157], v[72:73]
	v_pk_mul_f32 v[4:5], v[154:155], v[70:71]
	v_pk_mul_f32 v[6:7], v[160:161], v[72:73]
	v_pk_mul_f32 v[8:9], v[158:159], v[70:71]
	v_pk_fma_f32 v[2:3], v[160:161], v[68:69], v[2:3] neg_lo:[0,0,1] neg_hi:[0,0,1]
	v_pk_fma_f32 v[4:5], v[158:159], v[66:67], v[4:5] neg_lo:[0,0,1] neg_hi:[0,0,1]
	v_pk_fma_f32 v[172:173], v[156:157], v[68:69], v[6:7]
	v_pk_fma_f32 v[8:9], v[154:155], v[66:67], v[8:9]
	v_cndmask_b32_e64 v3, v161, v3, s[10:11]
	v_cndmask_b32_e64 v2, v160, v2, s[10:11]
	v_cndmask_b32_e64 v7, v159, v5, s[10:11]
	v_cndmask_b32_e64 v6, v158, v4, s[10:11]
	v_cndmask_b32_e64 v5, v157, v173, s[10:11]
	v_cndmask_b32_e64 v4, v156, v172, s[10:11]
	v_cndmask_b32_e64 v9, v155, v9, s[10:11]
	s_and_b64 vcc, exec, s[14:15]
	v_cndmask_b32_e64 v8, v154, v8, s[10:11]
	s_cbranch_vccnz .LBB0_567
	v_pk_mul_f32 v[2:3], v[2:3], s[56:57] op_sel_hi:[1,0]
	v_pk_mul_f32 v[6:7], v[6:7], s[56:57] op_sel_hi:[1,0]
	v_pk_mul_f32 v[4:5], v[4:5], s[56:57] op_sel_hi:[1,0]
	v_pk_mul_f32 v[8:9], v[8:9], s[56:57] op_sel_hi:[1,0]

.LBB0_575:
	s_andn2_b64 vcc, exec, s[4:5]
	s_cbranch_vccnz .LBB0_577
	v_sub_f32_e32 v2, 1.0, v162
	v_fma_f32 v2, v2, v160, v162
	v_sub_f32_e32 v3, 1.0, v166
	v_sub_f32_e32 v4, 1.0, v163
	v_fma_f32 v3, v3, v172, v166
	v_fma_f32 v4, v4, v161, v163
	v_sub_f32_e32 v5, 1.0, v167
	v_sub_f32_e32 v8, 1.0, v165
	v_log_f32_e32 v2, v2
	v_fma_f32 v5, v5, v173, v167
	v_sub_f32_e32 v6, 1.0, v164
	v_sub_f32_e32 v7, 1.0, v168
	v_fma_f32 v8, v8, v157, v165
	v_sub_f32_e32 v9, 1.0, v169
	v_log_f32_e32 v4, v4
	v_log_f32_e32 v157, v3
	v_fma_f32 v6, v6, v156, v164
	v_fma_f32 v7, v7, v158, v168
	v_fma_f32 v9, v9, v159, v169
	v_log_f32_e32 v8, v8
	v_log_f32_e32 v5, v5
	v_log_f32_e32 v156, v6
	v_log_f32_e32 v158, v7
	v_log_f32_e32 v159, v9
	v_mul_f32_e32 v2, 0x3f317218, v2
	v_max_f32_e32 v6, 0xc2a00000, v2
	v_mul_f32_e32 v2, 0x3f317218, v4
	v_mul_f32_e32 v4, 0x3f317218, v157
	v_mul_f32_e32 v3, 0x3f317218, v8
	v_max_f32_e32 v8, 0xc2a00000, v4
	v_mul_f32_e32 v4, 0x3f317218, v5
	v_max_f32_e32 v7, 0xc2a00000, v2
	v_mul_f32_e32 v2, 0x3f317218, v156
	v_max_f32_e32 v9, 0xc2a00000, v4
	v_mul_f32_e32 v4, 0x3f317218, v158
	v_mul_f32_e32 v5, 0x3f317218, v159
	v_max_f32_e32 v2, 0xc2a00000, v2
	v_max_f32_e32 v3, 0xc2a00000, v3
	v_max_f32_e32 v4, 0xc2a00000, v4
	v_max_f32_e32 v5, 0xc2a00000, v5

.LBB0_578:
	s_andn2_b64 vcc, exec, s[4:5]
	s_cbranch_vccnz .LBB0_581
	v_pk_mul_f32 v[2:3], v[148:149], v[56:57]
	v_pk_mul_f32 v[4:5], v[146:147], v[54:55]
	v_pk_mul_f32 v[6:7], v[152:153], v[56:57]
	v_pk_mul_f32 v[8:9], v[150:151], v[54:55]
	v_pk_fma_f32 v[2:3], v[152:153], v[52:53], v[2:3] neg_lo:[0,0,1] neg_hi:[0,0,1]
	v_pk_fma_f32 v[4:5], v[150:151], v[50:51], v[4:5] neg_lo:[0,0,1] neg_hi:[0,0,1]
	v_pk_fma_f32 v[156:157], v[148:149], v[52:53], v[6:7]
	v_pk_fma_f32 v[8:9], v[146:147], v[50:51], v[8:9]
	v_cndmask_b32_e64 v3, v153, v3, s[10:11]
	v_cndmask_b32_e64 v2, v152, v2, s[10:11]
	v_cndmask_b32_e64 v7, v151, v5, s[10:11]
	v_cndmask_b32_e64 v6, v150, v4, s[10:11]
	v_cndmask_b32_e64 v5, v149, v157, s[10:11]
	v_cndmask_b32_e64 v4, v148, v156, s[10:11]
	v_cndmask_b32_e64 v9, v147, v9, s[10:11]
	s_and_b64 vcc, exec, s[14:15]
	v_cndmask_b32_e64 v8, v146, v8, s[10:11]
	s_cbranch_vccnz .LBB0_581
	v_pk_mul_f32 v[2:3], v[2:3], s[56:57] op_sel_hi:[1,0]
	v_pk_mul_f32 v[6:7], v[6:7], s[56:57] op_sel_hi:[1,0]
	v_pk_mul_f32 v[4:5], v[4:5], s[56:57] op_sel_hi:[1,0]
	v_pk_mul_f32 v[8:9], v[8:9], s[56:57] op_sel_hi:[1,0]

.LBB0_589:
	s_andn2_b64 vcc, exec, s[4:5]
	s_cbranch_vccnz .LBB0_591
	v_sub_f32_e32 v2, 1.0, v162
	v_fmac_f32_e32 v162, v2, v152
	v_sub_f32_e32 v2, 1.0, v166
	v_fmac_f32_e32 v166, v2, v156
	v_sub_f32_e32 v2, 1.0, v163
	v_fmac_f32_e32 v163, v2, v153
	v_sub_f32_e32 v2, 1.0, v167
	v_fmac_f32_e32 v167, v2, v157
	v_sub_f32_e32 v2, 1.0, v164
	v_fmac_f32_e32 v164, v2, v148
	v_sub_f32_e32 v2, 1.0, v168
	v_fmac_f32_e32 v168, v2, v150
	v_sub_f32_e32 v2, 1.0, v165
	v_fmac_f32_e32 v165, v2, v149
	v_sub_f32_e32 v2, 1.0, v169
	v_fmac_f32_e32 v169, v2, v151
	v_log_f32_e32 v2, v162
	v_log_f32_e32 v3, v163
	v_log_f32_e32 v4, v164
	v_log_f32_e32 v8, v166
	v_log_f32_e32 v9, v167
	v_log_f32_e32 v5, v165
	v_log_f32_e32 v148, v168
	v_log_f32_e32 v149, v169
	v_mul_f32_e32 v2, 0x3f317218, v2
	v_max_f32_e32 v6, 0xc2a00000, v2
	v_mul_f32_e32 v2, 0x3f317218, v3
	v_max_f32_e32 v7, 0xc2a00000, v2
	v_mul_f32_e32 v2, 0x3f317218, v4
	v_mul_f32_e32 v4, 0x3f317218, v8
	v_max_f32_e32 v8, 0xc2a00000, v4
	v_mul_f32_e32 v4, 0x3f317218, v9
	v_mul_f32_e32 v3, 0x3f317218, v5
	v_max_f32_e32 v9, 0xc2a00000, v4
	v_mul_f32_e32 v4, 0x3f317218, v148
	v_mul_f32_e32 v5, 0x3f317218, v149
	v_max_f32_e32 v2, 0xc2a00000, v2
	v_max_f32_e32 v3, 0xc2a00000, v3
	v_max_f32_e32 v4, 0xc2a00000, v4
	v_max_f32_e32 v5, 0xc2a00000, v5

.LBB0_592:
	s_andn2_b64 vcc, exec, s[4:5]
	s_cbranch_vccnz .LBB0_595
	v_pk_mul_f32 v[2:3], v[132:133], v[40:41]
	v_pk_mul_f32 v[4:5], v[130:131], v[38:39]
	v_pk_mul_f32 v[6:7], v[136:137], v[40:41]
	v_pk_mul_f32 v[8:9], v[134:135], v[38:39]
	v_pk_fma_f32 v[2:3], v[136:137], v[36:37], v[2:3] neg_lo:[0,0,1] neg_hi:[0,0,1]
	v_pk_fma_f32 v[4:5], v[134:135], v[34:35], v[4:5] neg_lo:[0,0,1] neg_hi:[0,0,1]
	v_pk_fma_f32 v[148:149], v[132:133], v[36:37], v[6:7]
	v_pk_fma_f32 v[8:9], v[130:131], v[34:35], v[8:9]
	v_cndmask_b32_e64 v3, v137, v3, s[10:11]
	v_cndmask_b32_e64 v2, v136, v2, s[10:11]
	v_cndmask_b32_e64 v7, v135, v5, s[10:11]
	v_cndmask_b32_e64 v6, v134, v4, s[10:11]
	v_cndmask_b32_e64 v5, v133, v149, s[10:11]
	v_cndmask_b32_e64 v4, v132, v148, s[10:11]
	v_cndmask_b32_e64 v9, v131, v9, s[10:11]
	s_and_b64 vcc, exec, s[14:15]
	v_cndmask_b32_e64 v8, v130, v8, s[10:11]
	s_cbranch_vccnz .LBB0_595
	v_pk_mul_f32 v[2:3], v[2:3], s[56:57] op_sel_hi:[1,0]
	v_pk_mul_f32 v[6:7], v[6:7], s[56:57] op_sel_hi:[1,0]
	v_pk_mul_f32 v[4:5], v[4:5], s[56:57] op_sel_hi:[1,0]
	v_pk_mul_f32 v[8:9], v[8:9], s[56:57] op_sel_hi:[1,0]

.LBB0_618:
	v_exp_f32_e32 v0, v2
	v_exp_f32_e32 v2, v3
	v_exp_f32_e32 v3, v4
	v_exp_f32_e32 v4, v5
	v_exp_f32_e32 v5, v6
	v_exp_f32_e32 v6, v7
	v_exp_f32_e32 v7, v8
	v_exp_f32_e32 v8, v9
	v_add_f32_e32 v0, 1.0, v0
	v_add_f32_e32 v2, 1.0, v2
	v_add_f32_e32 v3, 1.0, v3
	v_add_f32_e32 v4, 1.0, v4
	v_add_f32_e32 v5, 1.0, v5
	v_add_f32_e32 v6, 1.0, v6
	v_add_f32_e32 v7, 1.0, v7
	v_add_f32_e32 v8, 1.0, v8
	v_rcp_f32_e32 v112, v0
	v_rcp_f32_e32 v113, v2
	v_rcp_f32_e32 v108, v3
	v_rcp_f32_e32 v109, v4
	v_rcp_f32_e32 v138, v5
	v_rcp_f32_e32 v139, v6
	v_rcp_f32_e32 v110, v7
	v_rcp_f32_e32 v111, v8
	s_andn2_b64 vcc, exec, s[38:39]
	s_mov_b64 s[4:5], -1
	s_cbranch_vccnz .LBB0_620
	v_pk_mul_f32 v[4:5], v[96:97], v[108:109]
	v_pk_mul_f32 v[8:9], v[94:95], v[112:113]
	v_pk_mul_f32 v[2:3], v[92:93], v[110:111]
	v_pk_mul_f32 v[6:7], v[90:91], v[138:139]
	s_mov_b64 s[4:5], 0

.LBB0_623:
	s_andn2_b64 vcc, exec, s[4:5]
	s_cbranch_vccnz .LBB0_625
	v_pk_mul_f32 v[2:3], v[92:93], v[128:129]
	v_pk_mul_f32 v[4:5], v[90:91], v[126:127]
	v_pk_mul_f32 v[6:7], v[96:97], v[128:129]
	v_pk_mul_f32 v[8:9], v[94:95], v[126:127]
	v_pk_fma_f32 v[2:3], v[96:97], v[124:125], v[2:3] neg_lo:[0,0,1] neg_hi:[0,0,1]
	v_pk_fma_f32 v[4:5], v[94:95], v[122:123], v[4:5] neg_lo:[0,0,1] neg_hi:[0,0,1]
	v_pk_fma_f32 v[6:7], v[92:93], v[124:125], v[6:7]
	v_pk_fma_f32 v[8:9], v[90:91], v[122:123], v[8:9]
	v_cndmask_b32_e64 v97, v97, v3, s[10:11]
	v_cndmask_b32_e64 v96, v96, v2, s[10:11]
	v_cndmask_b32_e64 v95, v95, v5, s[10:11]
	v_cndmask_b32_e64 v94, v94, v4, s[10:11]
	v_cndmask_b32_e64 v3, v93, v7, s[10:11]
	v_cndmask_b32_e64 v2, v92, v6, s[10:11]
	v_cndmask_b32_e64 v5, v91, v9, s[10:11]
	v_cndmask_b32_e64 v4, v90, v8, s[10:11]
	v_pk_mul_f32 v[2:3], v[2:3], s[56:57] op_sel_hi:[1,0]
	v_pk_mul_f32 v[6:7], v[4:5], s[56:57] op_sel_hi:[1,0]
	v_pk_mul_f32 v[4:5], v[96:97], s[56:57] op_sel_hi:[1,0]
	v_pk_mul_f32 v[8:9], v[94:95], s[56:57] op_sel_hi:[1,0]

.LBB0_633:
	s_andn2_b64 vcc, exec, s[4:5]
	s_cbranch_vccnz .LBB0_635
	v_sub_f32_e32 v0, 1.0, v130
	v_fma_f32 v0, v0, v94, v130
	v_sub_f32_e32 v3, 1.0, v131
	v_fma_f32 v3, v3, v95, v131
	v_sub_f32_e32 v5, 1.0, v132
	v_log_f32_e32 v0, v0
	v_fma_f32 v5, v5, v90, v132
	v_sub_f32_e32 v7, 1.0, v133
	v_log_f32_e32 v3, v3
	v_sub_f32_e32 v2, 1.0, v134
	v_fma_f32 v7, v7, v91, v133
	v_log_f32_e32 v5, v5
	v_fma_f32 v2, v2, v96, v134
	v_sub_f32_e32 v4, 1.0, v135
	v_sub_f32_e32 v8, 1.0, v137
	v_log_f32_e32 v7, v7
	v_fma_f32 v4, v4, v97, v135
	v_sub_f32_e32 v6, 1.0, v136
	v_fma_f32 v8, v8, v93, v137
	v_log_f32_e32 v2, v2
	v_mul_f32_e32 v0, 0x3f317218, v0
	v_fma_f32 v6, v6, v92, v136
	v_log_f32_e32 v90, v4
	v_log_f32_e32 v92, v8
	v_max_f32_e32 v8, 0xc2a00000, v0
	v_mul_f32_e32 v0, 0x3f317218, v3
	v_log_f32_e32 v91, v6
	v_max_f32_e32 v9, 0xc2a00000, v0
	v_mul_f32_e32 v0, 0x3f317218, v5
	v_max_f32_e32 v4, 0xc2a00000, v0
	v_mul_f32_e32 v0, 0x3f317218, v7
	v_max_f32_e32 v5, 0xc2a00000, v0
	v_mul_f32_e32 v0, 0x3f317218, v2
	v_max_f32_e32 v6, 0xc2a00000, v0
	v_mul_f32_e32 v0, 0x3f317218, v90
	v_max_f32_e32 v7, 0xc2a00000, v0
	v_mul_f32_e32 v0, 0x3f317218, v91
	v_max_f32_e32 v2, 0xc2a00000, v0
	v_mul_f32_e32 v0, 0x3f317218, v92
	v_max_f32_e32 v3, 0xc2a00000, v0

.LBB0_636:
	s_andn2_b64 vcc, exec, s[4:5]
	s_cbranch_vccnz .LBB0_638
	v_pk_mul_f32 v[2:3], v[76:77], v[120:121]
	v_pk_mul_f32 v[4:5], v[74:75], v[118:119]
	v_pk_mul_f32 v[6:7], v[80:81], v[120:121]
	v_pk_mul_f32 v[8:9], v[78:79], v[118:119]
	v_pk_fma_f32 v[2:3], v[80:81], v[116:117], v[2:3] neg_lo:[0,0,1] neg_hi:[0,0,1]
	v_pk_fma_f32 v[4:5], v[78:79], v[114:115], v[4:5] neg_lo:[0,0,1] neg_hi:[0,0,1]
	v_pk_fma_f32 v[6:7], v[76:77], v[116:117], v[6:7]
	v_pk_fma_f32 v[8:9], v[74:75], v[114:115], v[8:9]
	v_cndmask_b32_e64 v81, v81, v3, s[10:11]
	v_cndmask_b32_e64 v80, v80, v2, s[10:11]
	v_cndmask_b32_e64 v79, v79, v5, s[10:11]
	v_cndmask_b32_e64 v78, v78, v4, s[10:11]
	v_cndmask_b32_e64 v3, v77, v7, s[10:11]
	v_cndmask_b32_e64 v2, v76, v6, s[10:11]
	v_cndmask_b32_e64 v5, v75, v9, s[10:11]
	v_cndmask_b32_e64 v4, v74, v8, s[10:11]
	v_pk_mul_f32 v[2:3], v[2:3], s[56:57] op_sel_hi:[1,0]
	v_pk_mul_f32 v[6:7], v[4:5], s[56:57] op_sel_hi:[1,0]
	v_pk_mul_f32 v[4:5], v[80:81], s[56:57] op_sel_hi:[1,0]
	v_pk_mul_f32 v[8:9], v[78:79], s[56:57] op_sel_hi:[1,0]

.LBB0_646:
	s_andn2_b64 vcc, exec, s[4:5]
	s_cbranch_vccnz .LBB0_648
	v_sub_f32_e32 v0, 1.0, v130
	v_fma_f32 v0, v0, v78, v130
	v_sub_f32_e32 v3, 1.0, v131
	v_fma_f32 v3, v3, v79, v131
	v_sub_f32_e32 v5, 1.0, v132
	v_log_f32_e32 v0, v0
	v_fma_f32 v5, v5, v74, v132
	v_sub_f32_e32 v7, 1.0, v133
	v_log_f32_e32 v3, v3
	v_sub_f32_e32 v2, 1.0, v134
	v_fma_f32 v7, v7, v75, v133
	v_log_f32_e32 v5, v5
	v_fma_f32 v2, v2, v80, v134
	v_sub_f32_e32 v4, 1.0, v135
	v_sub_f32_e32 v8, 1.0, v137
	v_log_f32_e32 v7, v7
	v_fma_f32 v4, v4, v81, v135
	v_sub_f32_e32 v6, 1.0, v136
	v_fma_f32 v8, v8, v77, v137
	v_log_f32_e32 v2, v2
	v_mul_f32_e32 v0, 0x3f317218, v0
	v_fma_f32 v6, v6, v76, v136
	v_log_f32_e32 v74, v4
	v_log_f32_e32 v76, v8
	v_max_f32_e32 v8, 0xc2a00000, v0
	v_mul_f32_e32 v0, 0x3f317218, v3
	v_log_f32_e32 v75, v6
	v_max_f32_e32 v9, 0xc2a00000, v0
	v_mul_f32_e32 v0, 0x3f317218, v5
	v_max_f32_e32 v4, 0xc2a00000, v0
	v_mul_f32_e32 v0, 0x3f317218, v7
	v_max_f32_e32 v5, 0xc2a00000, v0
	v_mul_f32_e32 v0, 0x3f317218, v2
	v_max_f32_e32 v6, 0xc2a00000, v0
	v_mul_f32_e32 v0, 0x3f317218, v74
	v_max_f32_e32 v7, 0xc2a00000, v0
	v_mul_f32_e32 v0, 0x3f317218, v75
	v_max_f32_e32 v2, 0xc2a00000, v0
	v_mul_f32_e32 v0, 0x3f317218, v76
	v_max_f32_e32 v3, 0xc2a00000, v0

.LBB0_649:
	s_andn2_b64 vcc, exec, s[4:5]
	s_cbranch_vccnz .LBB0_651
	v_pk_mul_f32 v[2:3], v[60:61], v[104:105]
	v_pk_mul_f32 v[4:5], v[58:59], v[102:103]
	v_pk_mul_f32 v[6:7], v[64:65], v[104:105]
	v_pk_mul_f32 v[8:9], v[62:63], v[102:103]
	v_pk_fma_f32 v[2:3], v[64:65], v[100:101], v[2:3] neg_lo:[0,0,1] neg_hi:[0,0,1]
	v_pk_fma_f32 v[4:5], v[62:63], v[98:99], v[4:5] neg_lo:[0,0,1] neg_hi:[0,0,1]
	v_pk_fma_f32 v[6:7], v[60:61], v[100:101], v[6:7]
	v_pk_fma_f32 v[8:9], v[58:59], v[98:99], v[8:9]
	v_cndmask_b32_e64 v65, v65, v3, s[10:11]
	v_cndmask_b32_e64 v64, v64, v2, s[10:11]
	v_cndmask_b32_e64 v63, v63, v5, s[10:11]
	v_cndmask_b32_e64 v62, v62, v4, s[10:11]
	v_cndmask_b32_e64 v3, v61, v7, s[10:11]
	v_cndmask_b32_e64 v2, v60, v6, s[10:11]
	v_cndmask_b32_e64 v5, v59, v9, s[10:11]
	v_cndmask_b32_e64 v4, v58, v8, s[10:11]
	v_pk_mul_f32 v[2:3], v[2:3], s[56:57] op_sel_hi:[1,0]
	v_pk_mul_f32 v[6:7], v[4:5], s[56:57] op_sel_hi:[1,0]
	v_pk_mul_f32 v[4:5], v[64:65], s[56:57] op_sel_hi:[1,0]
	v_pk_mul_f32 v[8:9], v[62:63], s[56:57] op_sel_hi:[1,0]

.LBB0_659:
	s_andn2_b64 vcc, exec, s[4:5]
	s_cbranch_vccnz .LBB0_661
	v_sub_f32_e32 v0, 1.0, v130
	v_fma_f32 v0, v0, v62, v130
	v_sub_f32_e32 v3, 1.0, v131
	v_fma_f32 v3, v3, v63, v131
	v_sub_f32_e32 v5, 1.0, v132
	v_log_f32_e32 v0, v0
	v_fma_f32 v5, v5, v58, v132
	v_sub_f32_e32 v7, 1.0, v133
	v_log_f32_e32 v3, v3
	v_sub_f32_e32 v2, 1.0, v134
	v_fma_f32 v7, v7, v59, v133
	v_log_f32_e32 v5, v5
	v_fma_f32 v2, v2, v64, v134
	v_sub_f32_e32 v4, 1.0, v135
	v_sub_f32_e32 v8, 1.0, v137
	v_log_f32_e32 v7, v7
	v_fma_f32 v4, v4, v65, v135
	v_sub_f32_e32 v6, 1.0, v136
	v_fma_f32 v8, v8, v61, v137
	v_log_f32_e32 v2, v2
	v_mul_f32_e32 v0, 0x3f317218, v0
	v_fma_f32 v6, v6, v60, v136
	v_log_f32_e32 v58, v4
	v_log_f32_e32 v60, v8
	v_max_f32_e32 v8, 0xc2a00000, v0
	v_mul_f32_e32 v0, 0x3f317218, v3
	v_log_f32_e32 v59, v6
	v_max_f32_e32 v9, 0xc2a00000, v0
	v_mul_f32_e32 v0, 0x3f317218, v5
	v_max_f32_e32 v4, 0xc2a00000, v0
	v_mul_f32_e32 v0, 0x3f317218, v7
	v_max_f32_e32 v5, 0xc2a00000, v0
	v_mul_f32_e32 v0, 0x3f317218, v2
	v_max_f32_e32 v6, 0xc2a00000, v0
	v_mul_f32_e32 v0, 0x3f317218, v58
	v_max_f32_e32 v7, 0xc2a00000, v0
	v_mul_f32_e32 v0, 0x3f317218, v59
	v_max_f32_e32 v2, 0xc2a00000, v0
	v_mul_f32_e32 v0, 0x3f317218, v60
	v_max_f32_e32 v3, 0xc2a00000, v0

.LBB0_662:
	s_andn2_b64 vcc, exec, s[4:5]
	s_cbranch_vccnz .LBB0_664
	v_pk_mul_f32 v[2:3], v[44:45], v[88:89]
	v_pk_mul_f32 v[4:5], v[42:43], v[86:87]
	v_pk_mul_f32 v[6:7], v[48:49], v[88:89]
	v_pk_mul_f32 v[8:9], v[46:47], v[86:87]
	v_pk_fma_f32 v[2:3], v[48:49], v[84:85], v[2:3] neg_lo:[0,0,1] neg_hi:[0,0,1]
	v_pk_fma_f32 v[4:5], v[46:47], v[82:83], v[4:5] neg_lo:[0,0,1] neg_hi:[0,0,1]
	v_pk_fma_f32 v[6:7], v[44:45], v[84:85], v[6:7]
	v_pk_fma_f32 v[8:9], v[42:43], v[82:83], v[8:9]
	v_cndmask_b32_e64 v49, v49, v3, s[10:11]
	v_cndmask_b32_e64 v48, v48, v2, s[10:11]
	v_cndmask_b32_e64 v47, v47, v5, s[10:11]
	v_cndmask_b32_e64 v46, v46, v4, s[10:11]
	v_cndmask_b32_e64 v3, v45, v7, s[10:11]
	v_cndmask_b32_e64 v2, v44, v6, s[10:11]
	v_cndmask_b32_e64 v5, v43, v9, s[10:11]
	v_cndmask_b32_e64 v4, v42, v8, s[10:11]
	v_pk_mul_f32 v[2:3], v[2:3], s[56:57] op_sel_hi:[1,0]
	v_pk_mul_f32 v[6:7], v[4:5], s[56:57] op_sel_hi:[1,0]
	v_pk_mul_f32 v[4:5], v[48:49], s[56:57] op_sel_hi:[1,0]
	v_pk_mul_f32 v[8:9], v[46:47], s[56:57] op_sel_hi:[1,0]

.LBB0_672:
	s_andn2_b64 vcc, exec, s[4:5]
	s_cbranch_vccnz .LBB0_674
	v_sub_f32_e32 v0, 1.0, v130
	v_fma_f32 v0, v0, v46, v130
	v_sub_f32_e32 v3, 1.0, v131
	v_fma_f32 v3, v3, v47, v131
	v_sub_f32_e32 v5, 1.0, v132
	v_log_f32_e32 v0, v0
	v_fma_f32 v5, v5, v42, v132
	v_sub_f32_e32 v7, 1.0, v133
	v_log_f32_e32 v3, v3
	v_sub_f32_e32 v2, 1.0, v134
	v_fma_f32 v7, v7, v43, v133
	v_log_f32_e32 v5, v5
	v_fma_f32 v2, v2, v48, v134
	v_sub_f32_e32 v4, 1.0, v135
	v_sub_f32_e32 v8, 1.0, v137
	v_log_f32_e32 v7, v7
	v_fma_f32 v4, v4, v49, v135
	v_sub_f32_e32 v6, 1.0, v136
	v_fma_f32 v8, v8, v45, v137
	v_log_f32_e32 v2, v2
	v_mul_f32_e32 v0, 0x3f317218, v0
	v_fma_f32 v6, v6, v44, v136
	v_log_f32_e32 v42, v4
	v_log_f32_e32 v44, v8
	v_max_f32_e32 v8, 0xc2a00000, v0
	v_mul_f32_e32 v0, 0x3f317218, v3
	v_log_f32_e32 v43, v6
	v_max_f32_e32 v9, 0xc2a00000, v0
	v_mul_f32_e32 v0, 0x3f317218, v5
	v_max_f32_e32 v4, 0xc2a00000, v0
	v_mul_f32_e32 v0, 0x3f317218, v7
	v_max_f32_e32 v5, 0xc2a00000, v0
	v_mul_f32_e32 v0, 0x3f317218, v2
	v_max_f32_e32 v6, 0xc2a00000, v0
	v_mul_f32_e32 v0, 0x3f317218, v42
	v_max_f32_e32 v7, 0xc2a00000, v0
	v_mul_f32_e32 v0, 0x3f317218, v43
	v_max_f32_e32 v2, 0xc2a00000, v0
	v_mul_f32_e32 v0, 0x3f317218, v44
	v_max_f32_e32 v3, 0xc2a00000, v0

.LBB0_675:
	s_andn2_b64 vcc, exec, s[4:5]
	s_cbranch_vccnz .LBB0_677
	v_pk_mul_f32 v[2:3], v[28:29], v[72:73]
	v_pk_mul_f32 v[4:5], v[26:27], v[70:71]
	v_pk_mul_f32 v[6:7], v[32:33], v[72:73]
	v_pk_mul_f32 v[8:9], v[30:31], v[70:71]
	v_pk_fma_f32 v[2:3], v[32:33], v[68:69], v[2:3] neg_lo:[0,0,1] neg_hi:[0,0,1]
	v_pk_fma_f32 v[4:5], v[30:31], v[66:67], v[4:5] neg_lo:[0,0,1] neg_hi:[0,0,1]
	v_pk_fma_f32 v[6:7], v[28:29], v[68:69], v[6:7]
	v_pk_fma_f32 v[8:9], v[26:27], v[66:67], v[8:9]
	v_cndmask_b32_e64 v33, v33, v3, s[10:11]
	v_cndmask_b32_e64 v32, v32, v2, s[10:11]
	v_cndmask_b32_e64 v31, v31, v5, s[10:11]
	v_cndmask_b32_e64 v30, v30, v4, s[10:11]
	v_cndmask_b32_e64 v3, v29, v7, s[10:11]
	v_cndmask_b32_e64 v2, v28, v6, s[10:11]
	v_cndmask_b32_e64 v5, v27, v9, s[10:11]
	v_cndmask_b32_e64 v4, v26, v8, s[10:11]
	v_pk_mul_f32 v[2:3], v[2:3], s[56:57] op_sel_hi:[1,0]
	v_pk_mul_f32 v[6:7], v[4:5], s[56:57] op_sel_hi:[1,0]
	v_pk_mul_f32 v[4:5], v[32:33], s[56:57] op_sel_hi:[1,0]
	v_pk_mul_f32 v[8:9], v[30:31], s[56:57] op_sel_hi:[1,0]

.LBB0_685:
	s_andn2_b64 vcc, exec, s[4:5]
	s_cbranch_vccnz .LBB0_687
	v_sub_f32_e32 v0, 1.0, v130
	v_fma_f32 v0, v0, v30, v130
	v_sub_f32_e32 v3, 1.0, v131
	v_fma_f32 v3, v3, v31, v131
	v_sub_f32_e32 v5, 1.0, v132
	v_log_f32_e32 v0, v0
	v_fma_f32 v5, v5, v26, v132
	v_sub_f32_e32 v7, 1.0, v133
	v_log_f32_e32 v3, v3
	v_sub_f32_e32 v2, 1.0, v134
	v_fma_f32 v7, v7, v27, v133
	v_log_f32_e32 v5, v5
	v_fma_f32 v2, v2, v32, v134
	v_sub_f32_e32 v4, 1.0, v135
	v_sub_f32_e32 v8, 1.0, v137
	v_log_f32_e32 v7, v7
	v_fma_f32 v4, v4, v33, v135
	v_sub_f32_e32 v6, 1.0, v136
	v_fma_f32 v8, v8, v29, v137
	v_log_f32_e32 v2, v2
	v_mul_f32_e32 v0, 0x3f317218, v0
	v_fma_f32 v6, v6, v28, v136
	v_log_f32_e32 v26, v4
	v_log_f32_e32 v28, v8
	v_max_f32_e32 v8, 0xc2a00000, v0
	v_mul_f32_e32 v0, 0x3f317218, v3
	v_log_f32_e32 v27, v6
	v_max_f32_e32 v9, 0xc2a00000, v0
	v_mul_f32_e32 v0, 0x3f317218, v5
	v_max_f32_e32 v4, 0xc2a00000, v0
	v_mul_f32_e32 v0, 0x3f317218, v7
	v_max_f32_e32 v5, 0xc2a00000, v0
	v_mul_f32_e32 v0, 0x3f317218, v2
	v_max_f32_e32 v6, 0xc2a00000, v0
	v_mul_f32_e32 v0, 0x3f317218, v26
	v_max_f32_e32 v7, 0xc2a00000, v0
	v_mul_f32_e32 v0, 0x3f317218, v27
	v_max_f32_e32 v2, 0xc2a00000, v0
	v_mul_f32_e32 v0, 0x3f317218, v28
	v_max_f32_e32 v3, 0xc2a00000, v0

.LBB0_688:
	s_andn2_b64 vcc, exec, s[4:5]
	s_cbranch_vccnz .LBB0_690
	v_pk_mul_f32 v[2:3], v[20:21], v[56:57]
	v_pk_mul_f32 v[4:5], v[18:19], v[54:55]
	v_pk_mul_f32 v[6:7], v[24:25], v[56:57]
	v_pk_mul_f32 v[8:9], v[22:23], v[54:55]
	v_pk_fma_f32 v[2:3], v[24:25], v[52:53], v[2:3] neg_lo:[0,0,1] neg_hi:[0,0,1]
	v_pk_fma_f32 v[4:5], v[22:23], v[50:51], v[4:5] neg_lo:[0,0,1] neg_hi:[0,0,1]
	v_pk_fma_f32 v[6:7], v[20:21], v[52:53], v[6:7]
	v_pk_fma_f32 v[8:9], v[18:19], v[50:51], v[8:9]
	v_cndmask_b32_e64 v25, v25, v3, s[10:11]
	v_cndmask_b32_e64 v24, v24, v2, s[10:11]
	v_cndmask_b32_e64 v23, v23, v5, s[10:11]
	v_cndmask_b32_e64 v22, v22, v4, s[10:11]
	v_cndmask_b32_e64 v3, v21, v7, s[10:11]
	v_cndmask_b32_e64 v2, v20, v6, s[10:11]
	v_cndmask_b32_e64 v5, v19, v9, s[10:11]
	v_cndmask_b32_e64 v4, v18, v8, s[10:11]
	v_pk_mul_f32 v[2:3], v[2:3], s[56:57] op_sel_hi:[1,0]
	v_pk_mul_f32 v[6:7], v[4:5], s[56:57] op_sel_hi:[1,0]
	v_pk_mul_f32 v[4:5], v[24:25], s[56:57] op_sel_hi:[1,0]
	v_pk_mul_f32 v[8:9], v[22:23], s[56:57] op_sel_hi:[1,0]

.LBB0_698:
	s_andn2_b64 vcc, exec, s[4:5]
	s_cbranch_vccnz .LBB0_700
	v_sub_f32_e32 v0, 1.0, v130
	v_fmac_f32_e32 v130, v0, v22
	v_sub_f32_e32 v0, 1.0, v134
	v_fmac_f32_e32 v134, v0, v24
	v_sub_f32_e32 v0, 1.0, v131
	v_fmac_f32_e32 v131, v0, v23
	v_sub_f32_e32 v0, 1.0, v135
	v_fmac_f32_e32 v135, v0, v25
	v_sub_f32_e32 v0, 1.0, v132
	v_fmac_f32_e32 v132, v0, v18
	v_sub_f32_e32 v0, 1.0, v136
	v_fmac_f32_e32 v136, v0, v20
	v_sub_f32_e32 v0, 1.0, v133
	v_fmac_f32_e32 v133, v0, v19
	v_sub_f32_e32 v0, 1.0, v137
	v_fmac_f32_e32 v137, v0, v21
	v_log_f32_e32 v0, v130
	v_log_f32_e32 v2, v131
	v_log_f32_e32 v3, v132
	v_log_f32_e32 v5, v133
	v_log_f32_e32 v6, v134
	v_mul_f32_e32 v0, 0x3f317218, v0
	v_log_f32_e32 v7, v135
	v_max_f32_e32 v8, 0xc2a00000, v0
	v_mul_f32_e32 v0, 0x3f317218, v2
	v_log_f32_e32 v18, v136
	v_max_f32_e32 v9, 0xc2a00000, v0
	v_mul_f32_e32 v0, 0x3f317218, v3
	v_log_f32_e32 v19, v137
	v_max_f32_e32 v4, 0xc2a00000, v0
	v_mul_f32_e32 v0, 0x3f317218, v5
	v_max_f32_e32 v5, 0xc2a00000, v0
	v_mul_f32_e32 v0, 0x3f317218, v6
	v_max_f32_e32 v6, 0xc2a00000, v0
	v_mul_f32_e32 v0, 0x3f317218, v7
	v_max_f32_e32 v7, 0xc2a00000, v0
	v_mul_f32_e32 v0, 0x3f317218, v18
	v_max_f32_e32 v2, 0xc2a00000, v0
	v_mul_f32_e32 v0, 0x3f317218, v19
	v_max_f32_e32 v3, 0xc2a00000, v0

.LBB0_701:
	s_andn2_b64 vcc, exec, s[4:5]
	s_cbranch_vccnz .LBB0_703
	v_pk_mul_f32 v[2:3], v[12:13], v[40:41]
	v_pk_mul_f32 v[4:5], v[10:11], v[38:39]
	v_pk_mul_f32 v[6:7], v[16:17], v[40:41]
	v_pk_mul_f32 v[8:9], v[14:15], v[38:39]
	v_pk_fma_f32 v[2:3], v[16:17], v[36:37], v[2:3] neg_lo:[0,0,1] neg_hi:[0,0,1]
	v_pk_fma_f32 v[4:5], v[14:15], v[34:35], v[4:5] neg_lo:[0,0,1] neg_hi:[0,0,1]
	v_pk_fma_f32 v[6:7], v[12:13], v[36:37], v[6:7]
	v_pk_fma_f32 v[8:9], v[10:11], v[34:35], v[8:9]
	v_cndmask_b32_e64 v17, v17, v3, s[10:11]
	v_cndmask_b32_e64 v16, v16, v2, s[10:11]
	v_cndmask_b32_e64 v15, v15, v5, s[10:11]
	v_cndmask_b32_e64 v14, v14, v4, s[10:11]
	v_cndmask_b32_e64 v3, v13, v7, s[10:11]
	v_cndmask_b32_e64 v2, v12, v6, s[10:11]
	v_cndmask_b32_e64 v5, v11, v9, s[10:11]
	v_cndmask_b32_e64 v4, v10, v8, s[10:11]
	v_pk_mul_f32 v[2:3], v[2:3], s[56:57] op_sel_hi:[1,0]
	v_pk_mul_f32 v[6:7], v[4:5], s[56:57] op_sel_hi:[1,0]
	v_pk_mul_f32 v[4:5], v[16:17], s[56:57] op_sel_hi:[1,0]
	v_pk_mul_f32 v[8:9], v[14:15], s[56:57] op_sel_hi:[1,0]

.LBB0_791:
	s_mov_b64 s[6:7], 0x10000
	v_add_co_u32_e32 v124, vcc, 0x10000, v152
	v_lshl_add_u64 v[122:123], v[152:153], 0, s[6:7]
	s_nop 0
	v_addc_co_u32_e32 v125, vcc, 0, v153, vcc
	global_load_dwordx4 v[126:129], v[124:125], off
	s_nop 0
	global_load_dwordx4 v[122:125], v[122:123], off offset:16
	s_waitcnt vmcnt(0)
.LBB0_792:
	v_pk_fma_f32 v[128:129], v[120:121], v[158:159], v[128:129]
	v_pk_fma_f32 v[126:127], v[118:119], v[142:143], v[126:127]
	v_pk_fma_f32 v[124:125], v[116:117], v[156:157], v[124:125]
	s_and_b64 vcc, exec, s[8:9]
	v_pk_fma_f32 v[122:123], v[114:115], v[144:145], v[122:123]
	s_cbranch_vccnz .LBB0_794
	v_add_co_u32_e32 v118, vcc, 0x8000, v150
	v_cvt_pk_bf16_f32 v114, v126, v127
	v_cvt_pk_bf16_f32 v115, v128, v129
	v_cvt_pk_bf16_f32 v116, v122, v123
	v_cvt_pk_bf16_f32 v117, v124, v125
	s_nop 1
	v_addc_co_u32_e32 v119, vcc, 0, v151, vcc
	global_store_dwordx4 v[118:119], v[114:117], off

.LBB0_797:
	s_mov_b64 s[6:7], 0x20000
	v_add_co_u32_e32 v116, vcc, 0x20000, v152
	v_lshl_add_u64 v[114:115], v[152:153], 0, s[6:7]
	s_nop 0
	v_addc_co_u32_e32 v117, vcc, 0, v153, vcc
	global_load_dwordx4 v[118:121], v[116:117], off
	s_nop 0
	global_load_dwordx4 v[114:117], v[114:115], off offset:16
	s_waitcnt vmcnt(0)
.LBB0_798:
	v_pk_fma_f32 v[120:121], v[112:113], v[158:159], v[120:121]
	v_pk_fma_f32 v[118:119], v[110:111], v[142:143], v[118:119]
	v_pk_fma_f32 v[116:117], v[108:109], v[156:157], v[116:117]
	s_and_b64 vcc, exec, s[8:9]
	v_pk_fma_f32 v[114:115], v[106:107], v[144:145], v[114:115]
	s_cbranch_vccnz .LBB0_800
	v_add_co_u32_e32 v110, vcc, 0x10000, v150
	v_cvt_pk_bf16_f32 v106, v118, v119
	v_cvt_pk_bf16_f32 v107, v120, v121
	v_cvt_pk_bf16_f32 v108, v114, v115
	v_cvt_pk_bf16_f32 v109, v116, v117
	s_nop 1
	v_addc_co_u32_e32 v111, vcc, 0, v151, vcc
	global_store_dwordx4 v[110:111], v[106:109], off

.LBB0_803:
	s_mov_b64 s[6:7], 0x30000
	v_add_co_u32_e32 v108, vcc, 0x30000, v152
	v_lshl_add_u64 v[106:107], v[152:153], 0, s[6:7]
	s_nop 0
	v_addc_co_u32_e32 v109, vcc, 0, v153, vcc
	global_load_dwordx4 v[110:113], v[108:109], off
	s_nop 0
	global_load_dwordx4 v[106:109], v[106:107], off offset:16
	s_waitcnt vmcnt(0)
.LBB0_804:
	v_pk_fma_f32 v[112:113], v[104:105], v[158:159], v[112:113]
	v_pk_fma_f32 v[110:111], v[102:103], v[142:143], v[110:111]
	v_pk_fma_f32 v[108:109], v[100:101], v[156:157], v[108:109]
	s_and_b64 vcc, exec, s[8:9]
	v_pk_fma_f32 v[106:107], v[98:99], v[144:145], v[106:107]
	s_cbranch_vccnz .LBB0_806
	v_add_co_u32_e32 v102, vcc, 0x18000, v150
	v_cvt_pk_bf16_f32 v98, v110, v111
	v_cvt_pk_bf16_f32 v99, v112, v113
	v_cvt_pk_bf16_f32 v100, v106, v107
	v_cvt_pk_bf16_f32 v101, v108, v109
	s_nop 1
	v_addc_co_u32_e32 v103, vcc, 0, v151, vcc
	global_store_dwordx4 v[102:103], v[98:101], off

.LBB0_808:
	s_andn2_b64 vcc, exec, s[12:13]
	s_cbranch_vccnz .LBB0_810
	s_mov_b64 s[6:7], 0x80000
	v_add_co_u32_e32 v100, vcc, 0x80000, v152
	v_lshl_add_u64 v[98:99], v[152:153], 0, s[6:7]
	s_nop 0
	v_addc_co_u32_e32 v101, vcc, 0, v153, vcc
	global_load_dwordx4 v[102:105], v[100:101], off
	s_nop 0
	global_load_dwordx4 v[98:101], v[98:99], off offset:16
	s_waitcnt vmcnt(0)
.LBB0_810:
	v_pk_fma_f32 v[104:105], v[96:97], v[158:159], v[104:105]
	v_pk_fma_f32 v[102:103], v[94:95], v[142:143], v[102:103]
	v_pk_fma_f32 v[100:101], v[92:93], v[156:157], v[100:101]
	s_and_b64 vcc, exec, s[8:9]
	v_pk_fma_f32 v[98:99], v[90:91], v[144:145], v[98:99]
	s_cbranch_vccnz .LBB0_812
	v_add_co_u32_e32 v94, vcc, 0x40000, v150
	v_cvt_pk_bf16_f32 v90, v102, v103
	v_cvt_pk_bf16_f32 v91, v104, v105
	v_cvt_pk_bf16_f32 v92, v98, v99
	v_cvt_pk_bf16_f32 v93, v100, v101
	s_nop 1
	v_addc_co_u32_e32 v95, vcc, 0, v151, vcc
	global_store_dwordx4 v[94:95], v[90:93], off

.LBB0_815:
	s_mov_b64 s[6:7], 0x90000
	v_add_co_u32_e32 v92, vcc, 0x90000, v152
	v_lshl_add_u64 v[90:91], v[152:153], 0, s[6:7]
	s_nop 0
	v_addc_co_u32_e32 v93, vcc, 0, v153, vcc
	global_load_dwordx4 v[94:97], v[92:93], off
	s_nop 0
	global_load_dwordx4 v[90:93], v[90:91], off offset:16
	s_waitcnt vmcnt(0)
.LBB0_816:
	v_pk_fma_f32 v[96:97], v[88:89], v[158:159], v[96:97]
	v_pk_fma_f32 v[94:95], v[86:87], v[142:143], v[94:95]
	v_pk_fma_f32 v[92:93], v[84:85], v[156:157], v[92:93]
	s_and_b64 vcc, exec, s[8:9]
	v_pk_fma_f32 v[90:91], v[82:83], v[144:145], v[90:91]
	s_cbranch_vccnz .LBB0_818
	v_add_co_u32_e32 v86, vcc, 0x48000, v150
	v_cvt_pk_bf16_f32 v82, v94, v95
	v_cvt_pk_bf16_f32 v83, v96, v97
	v_cvt_pk_bf16_f32 v84, v90, v91
	v_cvt_pk_bf16_f32 v85, v92, v93
	s_nop 1
	v_addc_co_u32_e32 v87, vcc, 0, v151, vcc
	global_store_dwordx4 v[86:87], v[82:85], off

.LBB0_821:
	s_mov_b64 s[6:7], 0xa0000
	v_add_co_u32_e32 v84, vcc, 0xa0000, v152
	v_lshl_add_u64 v[82:83], v[152:153], 0, s[6:7]
	s_nop 0
	v_addc_co_u32_e32 v85, vcc, 0, v153, vcc
	global_load_dwordx4 v[86:89], v[84:85], off
	s_nop 0
	global_load_dwordx4 v[82:85], v[82:83], off offset:16
	s_waitcnt vmcnt(0)
.LBB0_822:
	v_pk_fma_f32 v[88:89], v[80:81], v[158:159], v[88:89]
	v_pk_fma_f32 v[86:87], v[78:79], v[142:143], v[86:87]
	v_pk_fma_f32 v[84:85], v[76:77], v[156:157], v[84:85]
	s_and_b64 vcc, exec, s[8:9]
	v_pk_fma_f32 v[82:83], v[74:75], v[144:145], v[82:83]
	s_cbranch_vccnz .LBB0_824
	v_add_co_u32_e32 v78, vcc, 0x50000, v150
	v_cvt_pk_bf16_f32 v74, v86, v87
	v_cvt_pk_bf16_f32 v75, v88, v89
	v_cvt_pk_bf16_f32 v76, v82, v83
	v_cvt_pk_bf16_f32 v77, v84, v85
	s_nop 1
	v_addc_co_u32_e32 v79, vcc, 0, v151, vcc
	global_store_dwordx4 v[78:79], v[74:77], off

.LBB0_827:
	s_mov_b64 s[6:7], 0xb0000
	v_add_co_u32_e32 v76, vcc, 0xb0000, v152
	v_lshl_add_u64 v[74:75], v[152:153], 0, s[6:7]
	s_nop 0
	v_addc_co_u32_e32 v77, vcc, 0, v153, vcc
	global_load_dwordx4 v[78:81], v[76:77], off
	s_nop 0
	global_load_dwordx4 v[74:77], v[74:75], off offset:16
	s_waitcnt vmcnt(0)
.LBB0_828:
	v_pk_fma_f32 v[140:141], v[72:73], v[158:159], v[80:81]
	v_pk_fma_f32 v[142:143], v[70:71], v[142:143], v[78:79]
	v_pk_fma_f32 v[138:139], v[64:65], v[156:157], v[76:77]
	s_and_b64 vcc, exec, s[8:9]
	v_pk_fma_f32 v[144:145], v[62:63], v[144:145], v[74:75]
	s_cbranch_vccnz .LBB0_830
	v_add_co_u32_e32 v70, vcc, 0x58000, v150
	v_cvt_pk_bf16_f32 v62, v142, v143
	v_cvt_pk_bf16_f32 v63, v140, v141
	v_cvt_pk_bf16_f32 v64, v144, v145
	v_cvt_pk_bf16_f32 v65, v138, v139
	s_nop 1
	v_addc_co_u32_e32 v71, vcc, 0, v151, vcc
	global_store_dwordx4 v[70:71], v[62:65], off

.LBB0_839:
	s_mov_b64 s[6:7], 0x10200
	v_add_co_u32_e32 v60, vcc, 0x10000, v152
	v_lshl_add_u64 v[58:59], v[152:153], 0, s[6:7]
	s_nop 0
	v_addc_co_u32_e32 v61, vcc, 0, v153, vcc
	global_load_dwordx4 v[62:65], v[60:61], off offset:512
	s_nop 0
	global_load_dwordx4 v[58:61], v[58:59], off offset:16
	s_waitcnt vmcnt(0)
.LBB0_840:
	v_pk_fma_f32 v[64:65], v[56:57], v[160:161], v[64:65]
	v_pk_fma_f32 v[62:63], v[54:55], v[154:155], v[62:63]
	v_pk_fma_f32 v[60:61], v[52:53], v[158:159], v[60:61]
	s_and_b64 vcc, exec, s[8:9]
	v_pk_fma_f32 v[58:59], v[50:51], v[156:157], v[58:59]
	s_cbranch_vccnz .LBB0_842
	v_add_co_u32_e32 v54, vcc, 0x8000, v150
	v_cvt_pk_bf16_f32 v50, v62, v63
	v_cvt_pk_bf16_f32 v51, v64, v65
	v_cvt_pk_bf16_f32 v52, v58, v59
	v_cvt_pk_bf16_f32 v53, v60, v61
	s_nop 1
	v_addc_co_u32_e32 v55, vcc, 0, v151, vcc
	global_store_dwordx4 v[54:55], v[50:53], off offset:256

.LBB0_845:
	s_mov_b64 s[6:7], 0x20200
	v_add_co_u32_e32 v52, vcc, 0x20000, v152
	v_lshl_add_u64 v[50:51], v[152:153], 0, s[6:7]
	s_nop 0
	v_addc_co_u32_e32 v53, vcc, 0, v153, vcc
	global_load_dwordx4 v[54:57], v[52:53], off offset:512
	s_nop 0
	global_load_dwordx4 v[50:53], v[50:51], off offset:16
	s_waitcnt vmcnt(0)
.LBB0_846:
	v_pk_fma_f32 v[56:57], v[48:49], v[160:161], v[56:57]
	v_pk_fma_f32 v[54:55], v[46:47], v[154:155], v[54:55]
	v_pk_fma_f32 v[52:53], v[44:45], v[158:159], v[52:53]
	s_and_b64 vcc, exec, s[8:9]
	v_pk_fma_f32 v[50:51], v[42:43], v[156:157], v[50:51]
	s_cbranch_vccnz .LBB0_848
	v_add_co_u32_e32 v46, vcc, 0x10000, v150
	v_cvt_pk_bf16_f32 v42, v54, v55
	v_cvt_pk_bf16_f32 v43, v56, v57
	v_cvt_pk_bf16_f32 v44, v50, v51
	v_cvt_pk_bf16_f32 v45, v52, v53
	s_nop 1
	v_addc_co_u32_e32 v47, vcc, 0, v151, vcc
	global_store_dwordx4 v[46:47], v[42:45], off offset:256

.LBB0_851:
	s_mov_b64 s[6:7], 0x30200
	v_add_co_u32_e32 v44, vcc, 0x30000, v152
	v_lshl_add_u64 v[42:43], v[152:153], 0, s[6:7]
	s_nop 0
	v_addc_co_u32_e32 v45, vcc, 0, v153, vcc
	global_load_dwordx4 v[46:49], v[44:45], off offset:512
	s_nop 0
	global_load_dwordx4 v[42:45], v[42:43], off offset:16
	s_waitcnt vmcnt(0)
.LBB0_852:
	v_pk_fma_f32 v[48:49], v[40:41], v[160:161], v[48:49]
	v_pk_fma_f32 v[46:47], v[38:39], v[154:155], v[46:47]
	v_pk_fma_f32 v[44:45], v[36:37], v[158:159], v[44:45]
	s_and_b64 vcc, exec, s[8:9]
	v_pk_fma_f32 v[42:43], v[34:35], v[156:157], v[42:43]
	s_cbranch_vccnz .LBB0_854
	v_add_co_u32_e32 v38, vcc, 0x18000, v150
	v_cvt_pk_bf16_f32 v34, v46, v47
	v_cvt_pk_bf16_f32 v35, v48, v49
	v_cvt_pk_bf16_f32 v36, v42, v43
	v_cvt_pk_bf16_f32 v37, v44, v45
	s_nop 1
	v_addc_co_u32_e32 v39, vcc, 0, v151, vcc
	global_store_dwordx4 v[38:39], v[34:37], off offset:256

.LBB0_856:
	s_andn2_b64 vcc, exec, s[12:13]
	s_cbranch_vccnz .LBB0_858
	s_mov_b64 s[6:7], 0x80200
	v_add_co_u32_e32 v36, vcc, 0x80000, v152
	v_lshl_add_u64 v[34:35], v[152:153], 0, s[6:7]
	s_nop 0
	v_addc_co_u32_e32 v37, vcc, 0, v153, vcc
	global_load_dwordx4 v[38:41], v[36:37], off offset:512
	s_nop 0
	global_load_dwordx4 v[34:37], v[34:35], off offset:16
	s_waitcnt vmcnt(0)
.LBB0_858:
	v_pk_fma_f32 v[40:41], v[32:33], v[160:161], v[40:41]
	v_pk_fma_f32 v[38:39], v[30:31], v[154:155], v[38:39]
	v_pk_fma_f32 v[36:37], v[28:29], v[158:159], v[36:37]
	s_and_b64 vcc, exec, s[8:9]
	v_pk_fma_f32 v[34:35], v[26:27], v[156:157], v[34:35]
	s_cbranch_vccnz .LBB0_860
	v_add_co_u32_e32 v30, vcc, 0x40000, v150
	v_cvt_pk_bf16_f32 v26, v38, v39
	v_cvt_pk_bf16_f32 v27, v40, v41
	v_cvt_pk_bf16_f32 v28, v34, v35
	v_cvt_pk_bf16_f32 v29, v36, v37
	s_nop 1
	v_addc_co_u32_e32 v31, vcc, 0, v151, vcc
	global_store_dwordx4 v[30:31], v[26:29], off offset:256

.LBB0_863:
	s_mov_b64 s[6:7], 0x90200
	v_add_co_u32_e32 v28, vcc, 0x90000, v152
	v_lshl_add_u64 v[26:27], v[152:153], 0, s[6:7]
	s_nop 0
	v_addc_co_u32_e32 v29, vcc, 0, v153, vcc
	global_load_dwordx4 v[30:33], v[28:29], off offset:512
	s_nop 0
	global_load_dwordx4 v[26:29], v[26:27], off offset:16
	s_waitcnt vmcnt(0)
.LBB0_864:
	v_pk_fma_f32 v[32:33], v[24:25], v[160:161], v[32:33]
	v_pk_fma_f32 v[30:31], v[22:23], v[154:155], v[30:31]
	v_pk_fma_f32 v[28:29], v[20:21], v[158:159], v[28:29]
	s_and_b64 vcc, exec, s[8:9]
	v_pk_fma_f32 v[26:27], v[18:19], v[156:157], v[26:27]
	s_cbranch_vccnz .LBB0_866
	v_add_co_u32_e32 v22, vcc, 0x48000, v150
	v_cvt_pk_bf16_f32 v18, v30, v31
	v_cvt_pk_bf16_f32 v19, v32, v33
	v_cvt_pk_bf16_f32 v20, v26, v27
	v_cvt_pk_bf16_f32 v21, v28, v29
	s_nop 1
	v_addc_co_u32_e32 v23, vcc, 0, v151, vcc
	global_store_dwordx4 v[22:23], v[18:21], off offset:256

.LBB0_869:
	s_mov_b64 s[6:7], 0xa0200
	v_add_co_u32_e32 v20, vcc, 0xa0000, v152
	v_lshl_add_u64 v[18:19], v[152:153], 0, s[6:7]
	s_nop 0
	v_addc_co_u32_e32 v21, vcc, 0, v153, vcc
	global_load_dwordx4 v[22:25], v[20:21], off offset:512
	s_nop 0
	global_load_dwordx4 v[18:21], v[18:19], off offset:16
	s_waitcnt vmcnt(0)
.LBB0_870:
	v_pk_fma_f32 v[76:77], v[16:17], v[160:161], v[24:25]
	v_pk_fma_f32 v[78:79], v[14:15], v[154:155], v[22:23]
	v_pk_fma_f32 v[74:75], v[12:13], v[158:159], v[20:21]
	s_and_b64 vcc, exec, s[8:9]
	v_pk_fma_f32 v[80:81], v[10:11], v[156:157], v[18:19]
	s_cbranch_vccnz .LBB0_872
	v_add_co_u32_e32 v14, vcc, 0x50000, v150
	v_cvt_pk_bf16_f32 v10, v78, v79
	v_cvt_pk_bf16_f32 v11, v76, v77
	v_cvt_pk_bf16_f32 v12, v80, v81
	v_cvt_pk_bf16_f32 v13, v74, v75
	s_nop 1
	v_addc_co_u32_e32 v15, vcc, 0, v151, vcc
	global_store_dwordx4 v[14:15], v[10:13], off offset:256

.LBB0_875:
	s_mov_b64 s[6:7], 0xb0200
	v_add_co_u32_e32 v12, vcc, 0xb0000, v152
	v_lshl_add_u64 v[10:11], v[152:153], 0, s[6:7]
	s_nop 0
	v_addc_co_u32_e32 v13, vcc, 0, v153, vcc
	global_load_dwordx4 v[14:17], v[12:13], off offset:512
	s_nop 0
	global_load_dwordx4 v[10:13], v[10:11], off offset:16
	s_waitcnt vmcnt(0)
.LBB0_876:
	v_pk_fma_f32 v[152:153], v[8:9], v[160:161], v[16:17]
	v_pk_fma_f32 v[154:155], v[6:7], v[154:155], v[14:15]
	v_pk_fma_f32 v[146:147], v[4:5], v[158:159], v[12:13]
	s_and_b64 vcc, exec, s[8:9]
	v_pk_fma_f32 v[156:157], v[2:3], v[156:157], v[10:11]
	s_cbranch_vccnz .LBB0_878
	v_add_co_u32_e32 v6, vcc, 0x58000, v150
	v_cvt_pk_bf16_f32 v2, v154, v155
	v_cvt_pk_bf16_f32 v3, v152, v153
	v_cvt_pk_bf16_f32 v4, v156, v157
	v_cvt_pk_bf16_f32 v5, v146, v147
	s_nop 1
	v_addc_co_u32_e32 v7, vcc, 0, v151, vcc
	global_store_dwordx4 v[6:7], v[2:5], off offset:256

.LBB0_1018:
	s_and_b64 vcc, exec, s[2:3]
	s_cbranch_vccz .LBB0_1086
	s_waitcnt vmcnt(0)
	v_mov_b32_e32 v2, v244
	s_cmpk_gt_i32 s94, 0xff
	v_ashrrev_i32_e32 v4, 6, v2
	v_readfirstlane_b32 s16, v2
	v_readfirstlane_b32 s6, v4
	s_cbranch_scc1 .LBB0_1027
	s_movk_i32 s2, 0xc00
	v_cmp_gt_i32_e32 vcc, s2, v2
	s_waitcnt lgkmcnt(0)
	s_barrier
	s_and_saveexec_b64 s[2:3], vcc
	s_cbranch_execz .LBB0_1023
	s_load_dwordx2 s[10:11], s[0:1], 0x8
	s_load_dwordx2 s[8:9], s[0:1], 0x18
	v_lshlrev_b32_e32 v5, 2, v2
	s_waitcnt lgkmcnt(0)
	s_add_u32 s98, s10, 0x1000
	s_addc_u32 s99, s11, 0
	global_load_dword v0, v5, s[10:11]
	global_load_dword v3, v5, s[10:11] offset:2048
	global_load_dword v6, v5, s[98:99]
	global_load_dword v7, v5, s[98:99] offset:2048
	global_load_dword v38, v5, s[8:9]
	global_load_dword v39, v5, s[8:9] offset:2048
	s_waitcnt vmcnt(0)
	v_mul_f32_e32 v8, 0xbfb8aa3b, v0
	v_exp_f32_e32 v8, v8
	s_nop 0
	v_add_f32_e32 v8, 1.0, v8
	v_div_scale_f32 v9, s[8:9], v8, v8, v0
	v_rcp_f32_e32 v10, v9
	v_div_scale_f32 v11, vcc, v0, v8, v0
	v_fma_f32 v12, -v9, v10, 1.0
	v_fmac_f32_e32 v10, v12, v10
	v_mul_f32_e32 v12, v11, v10
	v_fma_f32 v13, -v9, v12, v11
	v_fmac_f32_e32 v12, v13, v10
	v_fma_f32 v9, -v9, v12, v11
	v_div_fmas_f32 v9, v9, v10, v12
	v_div_fixup_f32 v0, v9, v8, v0
	ds_write_b32 v5, v0
	v_mul_f32_e32 v8, 0xbfb8aa3b, v3
	v_exp_f32_e32 v8, v8
	s_nop 0
	v_add_f32_e32 v8, 1.0, v8
	v_div_scale_f32 v9, s[8:9], v8, v8, v3
	v_rcp_f32_e32 v10, v9
	v_div_scale_f32 v11, vcc, v3, v8, v3
	v_fma_f32 v12, -v9, v10, 1.0
	v_fmac_f32_e32 v10, v12, v10
	v_mul_f32_e32 v12, v11, v10
	v_fma_f32 v13, -v9, v12, v11
	v_fmac_f32_e32 v12, v13, v10
	v_fma_f32 v9, -v9, v12, v11
	v_div_fmas_f32 v9, v9, v10, v12
	v_div_fixup_f32 v3, v9, v8, v3
	ds_write_b32 v5, v3 offset:2048
	v_mul_f32_e32 v8, 0xbfb8aa3b, v6
	v_exp_f32_e32 v8, v8
	s_nop 0
	v_add_f32_e32 v8, 1.0, v8
	v_div_scale_f32 v9, s[8:9], v8, v8, v6
	v_rcp_f32_e32 v10, v9
	v_div_scale_f32 v11, vcc, v6, v8, v6
	v_fma_f32 v12, -v9, v10, 1.0
	v_fmac_f32_e32 v10, v12, v10
	v_mul_f32_e32 v12, v11, v10
	v_fma_f32 v13, -v9, v12, v11
	v_fmac_f32_e32 v12, v13, v10
	v_fma_f32 v9, -v9, v12, v11
	v_div_fmas_f32 v9, v9, v10, v12
	v_div_fixup_f32 v6, v9, v8, v6
	ds_write_b32 v5, v6 offset:4096
	v_mul_f32_e32 v8, 0xbfb8aa3b, v7
	v_exp_f32_e32 v8, v8
	s_nop 0
	v_add_f32_e32 v8, 1.0, v8
	v_div_scale_f32 v9, s[8:9], v8, v8, v7
	v_rcp_f32_e32 v10, v9
	v_div_scale_f32 v11, vcc, v7, v8, v7
	v_fma_f32 v12, -v9, v10, 1.0
	v_fmac_f32_e32 v10, v12, v10
	v_mul_f32_e32 v12, v11, v10
	v_fma_f32 v13, -v9, v12, v11
	v_fmac_f32_e32 v12, v13, v10
	v_fma_f32 v9, -v9, v12, v11
	v_div_fmas_f32 v9, v9, v10, v12
	v_div_fixup_f32 v7, v9, v8, v7
	ds_write_b32 v5, v7 offset:6144
	v_mul_f32_e32 v8, 0xbfb8aa3b, v38
	v_exp_f32_e32 v8, v8
	s_nop 0
	v_add_f32_e32 v8, 1.0, v8
	v_div_scale_f32 v9, s[8:9], v8, v8, v38
	v_rcp_f32_e32 v10, v9
	v_div_scale_f32 v11, vcc, v38, v8, v38
	v_fma_f32 v12, -v9, v10, 1.0
	v_fmac_f32_e32 v10, v12, v10
	v_mul_f32_e32 v12, v11, v10
	v_fma_f32 v13, -v9, v12, v11
	v_fmac_f32_e32 v12, v13, v10
	v_fma_f32 v9, -v9, v12, v11
	v_div_fmas_f32 v9, v9, v10, v12
	v_div_fixup_f32 v38, v9, v8, v38
	ds_write_b32 v5, v38 offset:8192
	v_mul_f32_e32 v8, 0xbfb8aa3b, v39
	v_exp_f32_e32 v8, v8
	s_nop 0
	v_add_f32_e32 v8, 1.0, v8
	v_div_scale_f32 v9, s[8:9], v8, v8, v39
	v_rcp_f32_e32 v10, v9
	v_div_scale_f32 v11, vcc, v39, v8, v39
	v_fma_f32 v12, -v9, v10, 1.0
	v_fmac_f32_e32 v10, v12, v10
	v_mul_f32_e32 v12, v11, v10
	v_fma_f32 v13, -v9, v12, v11
	v_fmac_f32_e32 v12, v13, v10
	v_fma_f32 v9, -v9, v12, v11
	v_div_fmas_f32 v9, v9, v10, v12
	v_div_fixup_f32 v39, v9, v8, v39
	ds_write_b32 v5, v39 offset:10240

.LBB0_1138:
	v_readlane_b32 s2, v254, 39
	v_readlane_b32 s3, v254, 40
	s_and_b64 vcc, exec, s[2:3]
	s_cbranch_vccz .LBB0_1017
	s_and_b64 s[2:3], s[12:13], exec
	s_cselect_b32 s2, 0, 0xc0
	s_movk_i32 s3, 0x54
	s_cselect_b32 s3, s3, 0x100
	s_add_i32 s14, s14, s2
	s_cmp_lt_i32 s14, s3
	s_waitcnt vmcnt(0)
	s_barrier
	s_cbranch_scc0 .LBB0_1017
	v_mov_b32_e32 v4, v244
	s_movk_i32 s2, 0xc00
	v_ashrrev_i32_e32 v2, 6, v4
	v_cmp_gt_i32_e32 vcc, s2, v4
	v_readfirstlane_b32 s6, v2
	s_barrier
	s_and_saveexec_b64 s[2:3], vcc
	s_cbranch_execz .LBB0_1143
	s_load_dwordx2 s[10:11], s[0:1], 0x8
	s_load_dwordx2 s[8:9], s[0:1], 0x18
	v_lshlrev_b32_e32 v3, 2, v4
	s_waitcnt lgkmcnt(0)
	s_add_u32 s98, s10, 0x1000
	s_addc_u32 s99, s11, 0
	global_load_dword v0, v3, s[10:11]
	global_load_dword v5, v3, s[10:11] offset:2048
	global_load_dword v6, v3, s[98:99]
	global_load_dword v7, v3, s[98:99] offset:2048
	global_load_dword v34, v3, s[8:9]
	global_load_dword v35, v3, s[8:9] offset:2048
	s_waitcnt vmcnt(0)
	v_mul_f32_e32 v8, 0xbfb8aa3b, v0
	v_exp_f32_e32 v8, v8
	s_nop 0
	v_add_f32_e32 v8, 1.0, v8
	v_div_scale_f32 v9, s[8:9], v8, v8, v0
	v_rcp_f32_e32 v10, v9
	v_div_scale_f32 v11, vcc, v0, v8, v0
	v_fma_f32 v12, -v9, v10, 1.0
	v_fmac_f32_e32 v10, v12, v10
	v_mul_f32_e32 v12, v11, v10
	v_fma_f32 v13, -v9, v12, v11
	v_fmac_f32_e32 v12, v13, v10
	v_fma_f32 v9, -v9, v12, v11
	v_div_fmas_f32 v9, v9, v10, v12
	v_div_fixup_f32 v0, v9, v8, v0
	ds_write_b32 v3, v0
	v_mul_f32_e32 v8, 0xbfb8aa3b, v5
	v_exp_f32_e32 v8, v8
	s_nop 0
	v_add_f32_e32 v8, 1.0, v8
	v_div_scale_f32 v9, s[8:9], v8, v8, v5
	v_rcp_f32_e32 v10, v9
	v_div_scale_f32 v11, vcc, v5, v8, v5
	v_fma_f32 v12, -v9, v10, 1.0
	v_fmac_f32_e32 v10, v12, v10
	v_mul_f32_e32 v12, v11, v10
	v_fma_f32 v13, -v9, v12, v11
	v_fmac_f32_e32 v12, v13, v10
	v_fma_f32 v9, -v9, v12, v11
	v_div_fmas_f32 v9, v9, v10, v12
	v_div_fixup_f32 v5, v9, v8, v5
	ds_write_b32 v3, v5 offset:2048
	v_mul_f32_e32 v8, 0xbfb8aa3b, v6
	v_exp_f32_e32 v8, v8
	s_nop 0
	v_add_f32_e32 v8, 1.0, v8
	v_div_scale_f32 v9, s[8:9], v8, v8, v6
	v_rcp_f32_e32 v10, v9
	v_div_scale_f32 v11, vcc, v6, v8, v6
	v_fma_f32 v12, -v9, v10, 1.0
	v_fmac_f32_e32 v10, v12, v10
	v_mul_f32_e32 v12, v11, v10
	v_fma_f32 v13, -v9, v12, v11
	v_fmac_f32_e32 v12, v13, v10
	v_fma_f32 v9, -v9, v12, v11
	v_div_fmas_f32 v9, v9, v10, v12
	v_div_fixup_f32 v6, v9, v8, v6
	ds_write_b32 v3, v6 offset:4096
	v_mul_f32_e32 v8, 0xbfb8aa3b, v7
	v_exp_f32_e32 v8, v8
	s_nop 0
	v_add_f32_e32 v8, 1.0, v8
	v_div_scale_f32 v9, s[8:9], v8, v8, v7
	v_rcp_f32_e32 v10, v9
	v_div_scale_f32 v11, vcc, v7, v8, v7
	v_fma_f32 v12, -v9, v10, 1.0
	v_fmac_f32_e32 v10, v12, v10
	v_mul_f32_e32 v12, v11, v10
	v_fma_f32 v13, -v9, v12, v11
	v_fmac_f32_e32 v12, v13, v10
	v_fma_f32 v9, -v9, v12, v11
	v_div_fmas_f32 v9, v9, v10, v12
	v_div_fixup_f32 v7, v9, v8, v7
	ds_write_b32 v3, v7 offset:6144
	v_mul_f32_e32 v8, 0xbfb8aa3b, v34
	v_exp_f32_e32 v8, v8
	s_nop 0
	v_add_f32_e32 v8, 1.0, v8
	v_div_scale_f32 v9, s[8:9], v8, v8, v34
	v_rcp_f32_e32 v10, v9
	v_div_scale_f32 v11, vcc, v34, v8, v34
	v_fma_f32 v12, -v9, v10, 1.0
	v_fmac_f32_e32 v10, v12, v10
	v_mul_f32_e32 v12, v11, v10
	v_fma_f32 v13, -v9, v12, v11
	v_fmac_f32_e32 v12, v13, v10
	v_fma_f32 v9, -v9, v12, v11
	v_div_fmas_f32 v9, v9, v10, v12
	v_div_fixup_f32 v34, v9, v8, v34
	ds_write_b32 v3, v34 offset:8192
	v_mul_f32_e32 v8, 0xbfb8aa3b, v35
	v_exp_f32_e32 v8, v8
	s_nop 0
	v_add_f32_e32 v8, 1.0, v8
	v_div_scale_f32 v9, s[8:9], v8, v8, v35
	v_rcp_f32_e32 v10, v9
	v_div_scale_f32 v11, vcc, v35, v8, v35
	v_fma_f32 v12, -v9, v10, 1.0
	v_fmac_f32_e32 v10, v12, v10
	v_mul_f32_e32 v12, v11, v10
	v_fma_f32 v13, -v9, v12, v11
	v_fmac_f32_e32 v12, v13, v10
	v_fma_f32 v9, -v9, v12, v11
	v_div_fmas_f32 v9, v9, v10, v12
	v_div_fixup_f32 v35, v9, v8, v35
	ds_write_b32 v3, v35 offset:10240

.LBB0_1193:
	v_readlane_b32 s4, v254, 39
	v_readlane_b32 s5, v254, 40
	s_andn2_b64 vcc, exec, s[4:5]
	s_cbranch_vccnz .LBB0_716
	s_cmpk_lt_i32 s6, 0x6c
	s_waitcnt vmcnt(0) lgkmcnt(0)
	s_barrier
	s_cbranch_scc0 .LBB0_716
	v_readlane_b32 s4, v254, 41
	s_add_i32 s4, s6, s4
	v_mov_b32_e32 v4, v244
	s_add_i32 s12, s4, 0x154
	s_addk_i32 s4, 0x155
	s_cmp_lt_i32 s12, s4
	v_ashrrev_i32_e32 v2, 6, v4
	v_readlane_b32 s5, v254, 42
	v_readfirstlane_b32 s13, v2
	s_cbranch_scc0 .LBB0_716
	s_movk_i32 s4, 0xc00
	v_cmp_gt_i32_e32 vcc, s4, v4
	s_barrier
	s_and_saveexec_b64 s[4:5], vcc
	s_cbranch_execz .LBB0_1199
	s_load_dwordx2 s[10:11], s[0:1], 0x8
	s_load_dwordx2 s[8:9], s[0:1], 0x18
	v_lshlrev_b32_e32 v3, 2, v4
	s_waitcnt lgkmcnt(0)
	s_add_u32 s98, s10, 0x1000
	s_addc_u32 s99, s11, 0
	global_load_dword v0, v3, s[10:11]
	global_load_dword v5, v3, s[10:11] offset:2048
	global_load_dword v6, v3, s[98:99]
	global_load_dword v7, v3, s[98:99] offset:2048
	global_load_dword v34, v3, s[8:9]
	global_load_dword v35, v3, s[8:9] offset:2048
	s_waitcnt vmcnt(0)
	v_mul_f32_e32 v8, 0xbfb8aa3b, v0
	v_exp_f32_e32 v8, v8
	s_nop 0
	v_add_f32_e32 v8, 1.0, v8
	v_div_scale_f32 v9, s[8:9], v8, v8, v0
	v_rcp_f32_e32 v10, v9
	v_div_scale_f32 v11, vcc, v0, v8, v0
	v_fma_f32 v12, -v9, v10, 1.0
	v_fmac_f32_e32 v10, v12, v10
	v_mul_f32_e32 v12, v11, v10
	v_fma_f32 v13, -v9, v12, v11
	v_fmac_f32_e32 v12, v13, v10
	v_fma_f32 v9, -v9, v12, v11
	v_div_fmas_f32 v9, v9, v10, v12
	v_div_fixup_f32 v0, v9, v8, v0
	ds_write_b32 v3, v0
	v_mul_f32_e32 v8, 0xbfb8aa3b, v5
	v_exp_f32_e32 v8, v8
	s_nop 0
	v_add_f32_e32 v8, 1.0, v8
	v_div_scale_f32 v9, s[8:9], v8, v8, v5
	v_rcp_f32_e32 v10, v9
	v_div_scale_f32 v11, vcc, v5, v8, v5
	v_fma_f32 v12, -v9, v10, 1.0
	v_fmac_f32_e32 v10, v12, v10
	v_mul_f32_e32 v12, v11, v10
	v_fma_f32 v13, -v9, v12, v11
	v_fmac_f32_e32 v12, v13, v10
	v_fma_f32 v9, -v9, v12, v11
	v_div_fmas_f32 v9, v9, v10, v12
	v_div_fixup_f32 v5, v9, v8, v5
	ds_write_b32 v3, v5 offset:2048
	v_mul_f32_e32 v8, 0xbfb8aa3b, v6
	v_exp_f32_e32 v8, v8
	s_nop 0
	v_add_f32_e32 v8, 1.0, v8
	v_div_scale_f32 v9, s[8:9], v8, v8, v6
	v_rcp_f32_e32 v10, v9
	v_div_scale_f32 v11, vcc, v6, v8, v6
	v_fma_f32 v12, -v9, v10, 1.0
	v_fmac_f32_e32 v10, v12, v10
	v_mul_f32_e32 v12, v11, v10
	v_fma_f32 v13, -v9, v12, v11
	v_fmac_f32_e32 v12, v13, v10
	v_fma_f32 v9, -v9, v12, v11
	v_div_fmas_f32 v9, v9, v10, v12
	v_div_fixup_f32 v6, v9, v8, v6
	ds_write_b32 v3, v6 offset:4096
	v_mul_f32_e32 v8, 0xbfb8aa3b, v7
	v_exp_f32_e32 v8, v8
	s_nop 0
	v_add_f32_e32 v8, 1.0, v8
	v_div_scale_f32 v9, s[8:9], v8, v8, v7
	v_rcp_f32_e32 v10, v9
	v_div_scale_f32 v11, vcc, v7, v8, v7
	v_fma_f32 v12, -v9, v10, 1.0
	v_fmac_f32_e32 v10, v12, v10
	v_mul_f32_e32 v12, v11, v10
	v_fma_f32 v13, -v9, v12, v11
	v_fmac_f32_e32 v12, v13, v10
	v_fma_f32 v9, -v9, v12, v11
	v_div_fmas_f32 v9, v9, v10, v12
	v_div_fixup_f32 v7, v9, v8, v7
	ds_write_b32 v3, v7 offset:6144
	v_mul_f32_e32 v8, 0xbfb8aa3b, v34
	v_exp_f32_e32 v8, v8
	s_nop 0
	v_add_f32_e32 v8, 1.0, v8
	v_div_scale_f32 v9, s[8:9], v8, v8, v34
	v_rcp_f32_e32 v10, v9
	v_div_scale_f32 v11, vcc, v34, v8, v34
	v_fma_f32 v12, -v9, v10, 1.0
	v_fmac_f32_e32 v10, v12, v10
	v_mul_f32_e32 v12, v11, v10
	v_fma_f32 v13, -v9, v12, v11
	v_fmac_f32_e32 v12, v13, v10
	v_fma_f32 v9, -v9, v12, v11
	v_div_fmas_f32 v9, v9, v10, v12
	v_div_fixup_f32 v34, v9, v8, v34
	ds_write_b32 v3, v34 offset:8192
	v_mul_f32_e32 v8, 0xbfb8aa3b, v35
	v_exp_f32_e32 v8, v8
	s_nop 0
	v_add_f32_e32 v8, 1.0, v8
	v_div_scale_f32 v9, s[8:9], v8, v8, v35
	v_rcp_f32_e32 v10, v9
	v_div_scale_f32 v11, vcc, v35, v8, v35
	v_fma_f32 v12, -v9, v10, 1.0
	v_fmac_f32_e32 v10, v12, v10
	v_mul_f32_e32 v12, v11, v10
	v_fma_f32 v13, -v9, v12, v11
	v_fmac_f32_e32 v12, v13, v10
	v_fma_f32 v9, -v9, v12, v11
	v_div_fmas_f32 v9, v9, v10, v12
	v_div_fixup_f32 v35, v9, v8, v35
	ds_write_b32 v3, v35 offset:10240
